# W3A conversion items >= 7424 moved from P0 to the 64 workgroups idle in P1 (balanced 9 items per wave in P0, 7 per helper wave) on top of s1
# speedup vs baseline: 1.0058x; 1.0058x over previous
; #define LAS __attribute__((address_space(3)))
; #define SEAM(k) do { if (IN(k) && IN((k) + 1)) xcd_barrier(bar); } while (0)
; template <int JOB>
; __device__ __forceinline__ void conv_job(Frame& F, const Args& A, int rank, int nw) {
;     LAS float* scr = (LAS float*)(F.lds + RING_OFF + F.wave * 16896);
;     unsigned char* ws = A.ws;
;     constexpr int I_13 = (D / 128) * (FF / 32), I_2 = (FF / 128) * (D / 32), I_IN = (D / 64) * (NPROJ / 32), I_OUT = (D / 64) * (D / 32);
;     constexpr int N = (JOB == JOB_W1A || JOB == JOB_W3A || JOB == JOB_W1B || JOB == JOB_W3B) ? I_13 : (JOB == JOB_W2A || JOB == JOB_W2B) ? I_2 : (JOB == JOB_WIN) ? I_IN : I_OUT;
;     for (int it = rank; it < N; it += nw) {
;         if constexpr (JOB == JOB_W1A) p0_transpose_item8<1>(A.in[I_W1A], D, FF, ws + WS_W13A, S_W13, scr, it, F.lane);
;         if constexpr (JOB == JOB_W3A) p0_transpose_item8<2>(A.in[I_W3A], D, FF, ws + WS_W13A, S_W13, scr, it, F.lane);
; __global__ void __launch_bounds__(NWAVES * 64, 2) mk_fwd(Args args) {
;     ...
;     if (IN(0)) {
; #pragma unroll
;         for (int rep = 0; rep < REPS(0); ++rep) { if (rep) xcd_barrier(bar);  csilu_phase(F, args); { const int rank = F.vcu * NWAVES + F.wave, nw = F.G * NWAVES; conv_job<JOB_W1A>(F, args, rank, nw); conv_job<JOB_W3A>(F, args, rank, nw); }  } } SEAM(0);
;     if (IN(1)) {
; #pragma unroll
;         for (int rep = 0; rep < REPS(1); ++rep) { if (rep) xcd_barrier(bar); mod_chunk_partials(F, args, 0, F.vcu, F.G); } } SEAM(1);
.Lconv_entry:
	s_cmp_lg_u32 s98, 0
	s_cbranch_scc1 .Lconv_e2
	s_cmpk_eq_i32 s33, 0x100
	s_cbranch_scc0 .Lconv_e2
	s_movk_i32 s99, 0x1d00
.Lconv_e2:
	v_readlane_b32 s0, v252, 2
	s_lshl_b32 s0, s0, 3
	v_readlane_b32 s1, v252, 38
	s_add_i32 s0, s0, s1
	s_cmpk_gt_i32 s0, 0x2aff
	s_cbranch_scc1 .LBB0_22
	v_readlane_b32 s2, v252, 38
	s_mulk_i32 s2, 0x4200
	v_and_b32_e32 v18, 31, v0
	v_readlane_b32 s68, v252, 3
	s_add_i32 s2, s2, 0
	v_mov_b32_e32 v21, 0
	v_lshlrev_b32_e32 v20, 2, v18
	v_readlane_b32 s70, v252, 5
	v_readlane_b32 s71, v252, 6
	v_lshrrev_b32_e32 v3, 1, v0
	v_add_u32_e32 v2, s2, v20
	v_lshl_add_u64 v[22:23], s[70:71], 0, v[20:21]
	v_and_b32_e32 v20, 16, v3
	v_lshrrev_b32_e32 v19, 5, v162
	s_movk_i32 s2, 0x84
	v_mul_u32_u24_e32 v3, 0x84, v20
	v_mad_u32_u24 v24, v19, s2, v2
	s_lshl_b32 s6, s0, 5
	v_add_u32_e32 v25, v2, v3
	s_lshl_b32 s1, s33, 3
	s_lshl_b32 s7, s33, 8
	s_mov_b32 s8, 0xac00
	s_mov_b32 s9, 0xc3e00000
	v_mov_b32_e32 v26, 0x43e00000
	v_add_u32_e32 v27, 0x400, v24
	v_add_u32_e32 v28, 0x800, v24
	v_add_u32_e32 v29, 0xc00, v24
	v_add_u32_e32 v30, 0x1000, v24
	v_add_u32_e32 v31, 0x1400, v24
	v_add_u32_e32 v32, 0x1800, v24
	v_add_u32_e32 v33, 0x1c00, v24
	v_add_u32_e32 v34, 0x2000, v24
	v_add_u32_e32 v35, 0x2200, v24
	v_add_u32_e32 v36, 0x2400, v24
	v_add_u32_e32 v37, 0x2600, v24
	v_add_u32_e32 v38, 0x2800, v24
	v_add_u32_e32 v39, 0x2a00, v24
	v_add_u32_e32 v40, 0x2c00, v24
	v_add_u32_e32 v41, 0x2e00, v24
	v_add_u32_e32 v42, 0x3000, v24
	v_add_u32_e32 v43, 0x3200, v24
	v_add_u32_e32 v44, 0x3400, v24
	v_add_u32_e32 v45, 0x3600, v24
	v_add_u32_e32 v46, 0x3800, v24
	v_add_u32_e32 v47, 0x3a00, v24
	v_add_u32_e32 v48, 0x3c00, v24
	v_add_u32_e32 v49, 0x3e00, v24
	v_add_u32_e32 v50, 0x400, v25
	v_add_u32_e32 v51, 0x1000, v25
	v_add_u32_e32 v52, 0x1200, v25
	v_add_u32_e32 v53, 0x1400, v25
	v_add_u32_e32 v54, 0x1600, v25
	v_add_u32_e32 v55, 0x2000, v25
	v_add_u32_e32 v56, 0x2400, v25
	v_add_u32_e32 v57, 0x2800, v25
	v_add_u32_e32 v58, 0x3000, v25
	v_add_u32_e32 v59, 0x3200, v25
	v_add_u32_e32 v60, 0x3400, v25
	v_add_u32_e32 v61, 0x3600, v25
	v_add_u32_e32 v62, 0x3800, v25
	s_mov_b32 s14, s6
	s_mov_b32 s15, s0
	v_readlane_b32 s69, v252, 4
	v_readlane_b32 s72, v252, 7
	v_readlane_b32 s73, v252, 8
	v_readlane_b32 s74, v252, 9
	v_readlane_b32 s75, v252, 10
	v_readlane_b32 s76, v252, 11
	v_readlane_b32 s77, v252, 12
	v_readlane_b32 s78, v252, 13
	v_readlane_b32 s79, v252, 14
	v_readlane_b32 s80, v252, 15
	v_readlane_b32 s81, v252, 16
	v_readlane_b32 s82, v252, 17
	v_readlane_b32 s83, v252, 18
	s_cmp_lg_u32 s98, 1
	s_cbranch_scc1 .LBB0_19
	s_add_i32 s0, s0, 5888
	s_lshl_b32 s6, s0, 5
	s_movk_i32 s1, 0x200
	s_movk_i32 s7, 0x4000
	s_branch .Lw3a_pre
